# grid-barrier poll loops without s_sleep (tighter polling of the arrival counter); on top of v70
# speedup vs baseline: 1.0181x; 1.0181x over previous
; __device__ __forceinline__ void grid_barrier(unsigned* ctr, unsigned target, int wave) {
;     ...
;             __hip_atomic_fetch_add(ctr, 1u, __ATOMIC_RELAXED, __HIP_MEMORY_SCOPE_AGENT);
;             while (__hip_atomic_load(ctr, __ATOMIC_RELAXED, __HIP_MEMORY_SCOPE_AGENT) < target) __builtin_amdgcn_s_sleep(1);
;         }
.LBB0_17:
	s_nop 0
	global_load_dword v1, v0, s[4:5] sc1
	s_waitcnt vmcnt(0)
	v_cmp_gt_u32_e32 vcc, s94, v1
	s_cbranch_vccnz .LBB0_17

; __device__ __forceinline__ void grid_barrier(unsigned* ctr, unsigned target, int wave) {
;     ...
;             __hip_atomic_fetch_add(ctr, 1u, __ATOMIC_RELAXED, __HIP_MEMORY_SCOPE_AGENT);
;             while (__hip_atomic_load(ctr, __ATOMIC_RELAXED, __HIP_MEMORY_SCOPE_AGENT) < target) __builtin_amdgcn_s_sleep(1);
;         }
.LBB0_58:
	s_nop 0
	global_load_dword v1, v0, s[4:5] sc1
	s_waitcnt vmcnt(0)
	v_cmp_gt_u32_e32 vcc, s3, v1
	s_cbranch_vccnz .LBB0_58

; __device__ __forceinline__ void grid_barrier(unsigned* ctr, unsigned target, int wave) {
;     ...
;             __hip_atomic_fetch_add(ctr, 1u, __ATOMIC_RELAXED, __HIP_MEMORY_SCOPE_AGENT);
;             while (__hip_atomic_load(ctr, __ATOMIC_RELAXED, __HIP_MEMORY_SCOPE_AGENT) < target) __builtin_amdgcn_s_sleep(1);
;         }
.LBB0_828:
	s_nop 0
	global_load_dword v1, v0, s[60:61] sc1
	s_waitcnt vmcnt(0)
	v_cmp_gt_u32_e32 vcc, s3, v1
	s_cbranch_vccnz .LBB0_828

; __device__ __forceinline__ void grid_barrier(unsigned* ctr, unsigned target, int wave) {
;     ...
;             __hip_atomic_fetch_add(ctr, 1u, __ATOMIC_RELAXED, __HIP_MEMORY_SCOPE_AGENT);
;             while (__hip_atomic_load(ctr, __ATOMIC_RELAXED, __HIP_MEMORY_SCOPE_AGENT) < target) __builtin_amdgcn_s_sleep(1);
;         }
.LBB0_950:
	s_nop 0
	global_load_dword v1, v0, s[60:61] sc1
	s_waitcnt vmcnt(0)
	v_cmp_gt_u32_e32 vcc, s2, v1
	s_cbranch_vccnz .LBB0_950
